# all later-weights conversion (w_up_pool, w_up_hgrn, w_out, w_gate, w_up) moved into the load segments of the P1 GEMM K-loop; P4 recurrence no longer carries embedded conversion; P0 converts only w_in,
# speedup vs baseline: 1.0324x; 1.0079x over previous
; #define PG8_STAGE(bufoff, gbase, voff) do { _Pragma("unroll") for (int _i = 0; _i < 2; ++_i) \
;         __builtin_amdgcn_global_load_lds((const unsigned*)((const char*)(gbase) + (voff)[_i]), (PG8_LAS unsigned*)(lds + (bufoff) + ldsw + _i * 8192), 16, 0, 0); } while (0)
; #define PG8_WAIT_V(n) asm volatile("s_waitcnt vmcnt(" #n ")" ::: "memory")
; #define PG8_BAR __builtin_amdgcn_s_barrier()
; template <class Epi, class Sched, bool ALIGN_EPI = false, bool SP2 = false>
; __device__ __forceinline__ void gemm_phase(PG8_LAS unsigned char* lds, const Gemm g, const Sched& S, const Epi& E) {
;     ...
;         PG8_STAGE(PG8_SB(0, 0), cB, voffB); PG8_STAGE(PG8_SB(0, 1), cB + hstepB, voffB); PG8_STAGE(PG8_SA(0, 0), cA, voffA); PG8_STAGE(PG8_SA(0, 1), cA + hstepA, voffA);
;         if (wr == 1) PG8_BAR;
;         PG8_WAIT_V(2); PG8_BAR;
;         PG8_STAGE(PG8_SB(1, 0), cB + kstep, voffB); PG8_STAGE(PG8_SA(1, 0), cA + kstep, voffA); PG8_STAGE(PG8_SB(1, 1), cB + hstepB + kstep, voffB);
;         PG8_WAIT_V(6); PG8_BAR;
; __global__ void __launch_bounds__(NWAVES * 64, 2) fwd(Args args) {
;     ...
;     const float* x = args.in[0]; const float* g_mix = args.in[1]; const float* w_in = args.in[2]; const float* w_pg = args.in[3]; const float* pool_scale = args.in[4];
;     const float* lb_param = args.in[5]; const float* hgrn_norm = args.in[6]; const float* w_up_pool = args.in[7]; const float* w_up_hgrn = args.in[8]; const float* w_out = args.in[9];
;     const float* g_ffn = args.in[10]; const float* w_gate = args.in[11]; const float* w_up = args.in[12]; const float* w_down = args.in[13]; const float* g_final = args.in[14];
.LBB0_137:
	s_lshl_b32 s5, s5, 5
	s_mov_b64 s[18:19], 0x80
	s_and_b32 s5, s5, 0x60
	s_add_i32 m0, s55, 0x18000
	v_lshl_add_u64 v[8:9], v[8:9], 0, s[18:19]
	s_lshl_b32 s1, s4, 13
	s_lshl_b32 s22, s5, 7
	s_waitcnt vmcnt(2)
	s_barrier
	global_load_lds_dwordx4 v[8:9], off
	v_lshl_add_u64 v[4:5], v[4:5], 0, s[18:19]
	s_add_i32 m0, s55, 0x1a000
	s_add_i32 s75, s55, 0x8000
	s_add_i32 s76, s55, 0xa000
	global_load_lds_dwordx4 v[4:5], off
	v_lshl_add_u64 v[2:3], v[2:3], 0, s[18:19]
	s_mov_b32 m0, s75
	s_add_u32 s20, s8, 0x100080
	global_load_lds_dwordx4 v[2:3], off
	v_lshl_add_u64 v[2:3], v[6:7], 0, s[18:19]
	s_mov_b32 m0, s76
	s_addc_u32 s21, s9, 0
	global_load_lds_dwordx4 v[2:3], off
	s_add_i32 m0, s55, 0x1c000
	v_lshl_add_u64 v[2:3], s[20:21], 0, v[140:141]
	global_load_lds_dwordx4 v[2:3], off
	v_lshl_add_u64 v[2:3], s[20:21], 0, v[144:145]
	s_add_i32 m0, s55, 0x1e000
	v_and_b32_e32 v4, 32, v162
	global_load_lds_dwordx4 v[2:3], off
	v_and_b32_e32 v2, 15, v0
	v_lshlrev_b32_e32 v3, 1, v14
	v_lshl_or_b32 v163, s4, 6, v2
	v_lshl_or_b32 v2, v2, 6, v3
	v_bitop3_b32 v2, v2, s1, v4 bitop3:0xde
	v_lshlrev_b32_e32 v5, 6, v0
	s_movk_i32 s1, 0x3c0
	v_and_or_b32 v3, v5, s1, v3
	v_bitop3_b32 v164, s22, v3, v4 bitop3:0xf6
	v_lshlrev_b32_e32 v3, 10, v0
	v_and_b32_e32 v3, 0x60000, v3
	v_lshlrev_b32_e32 v4, 13, v12
	v_or3_b32 v3, v10, v3, v4
	s_cmpk_lt_u32 s14, 0x100
	v_add_u32_e32 v148, v3, v11
	v_lshlrev_b32_e32 v3, 6, v13
	s_waitcnt vmcnt(6)
	s_cselect_b64 s[20:21], -1, 0
	s_add_u32 s22, s62, 0x2000
	v_and_b32_e32 v3, 0xe0000, v3
	v_or_b32_e32 v165, s5, v14
	s_addc_u32 s23, s63, 0
	v_or3_b32 v3, v10, v3, v4
	s_add_i32 s83, 0, 0x10000
	s_add_i32 s89, 0, 0x14000
	v_or_b32_e32 v166, 0xffffec00, v165
	s_ashr_i32 s77, s74, 31
	s_ashr_i32 s81, s2, 31
	v_mov_b32_e32 v149, v147
	v_add_u32_e32 v150, v3, v11
	v_mov_b32_e32 v151, v147
	v_mov_b64_e32 v[152:153], 0x900
	v_mov_b64_e32 v[154:155], 0x8ff
	v_add_u32_e32 v167, s83, v164
	v_add_u32_e32 v168, s89, v164
	v_add_u32_e32 v169, 0, v2
	s_mov_b32 s90, 0xc2a00000
	s_mov_b32 s91, 0xc1f00000
	v_mov_b32_e32 v170, 0x42a00000
	v_mov_b32_e32 v171, 0x41f00000
	s_mov_b32 s92, 0
	s_barrier
	s_mov_b32 s32, 0
	s_mov_b32 s97, 0
	v_readlane_b32 s98, v244, 0
	v_readlane_b32 s99, v244, 1
	s_nop 3
	s_sub_u32 s98, s98, 0x98
	s_subb_u32 s99, s99, 0
	s_load_dwordx2 s[100:101], s[98:99], 0x58
	s_waitcnt lgkmcnt(0)
	v_writelane_b32 v245, s100, 0
	v_writelane_b32 v245, s101, 1
	s_nop 1
	s_load_dwordx2 s[100:101], s[98:99], 0x60
	s_waitcnt lgkmcnt(0)
	v_writelane_b32 v245, s100, 2
	v_writelane_b32 v245, s101, 3
	s_nop 1
	s_load_dwordx2 s[100:101], s[98:99], 0x50
	s_waitcnt lgkmcnt(0)
	v_writelane_b32 v245, s100, 4
	v_writelane_b32 v245, s101, 5
	s_nop 1
	s_load_dwordx2 s[100:101], s[98:99], 0x38
	s_waitcnt lgkmcnt(0)
	v_writelane_b32 v245, s100, 6
	v_writelane_b32 v245, s101, 7
	s_nop 1
	s_load_dwordx2 s[100:101], s[98:99], 0x40
	s_waitcnt lgkmcnt(0)
	v_writelane_b32 v245, s100, 8
	v_writelane_b32 v245, s101, 9
	s_nop 1
	s_load_dwordx2 s[100:101], s[98:99], 0x48
	s_waitcnt lgkmcnt(0)
	v_writelane_b32 v245, s100, 10
	v_writelane_b32 v245, s101, 11
	s_mul_hi_u32 s93, s80, 0xbe82fa0c
	s_lshr_b32 s93, s93, 8
	s_mul_i32 s85, s93, 0x158
	s_sub_i32 s85, s80, s85
	s_lshl_b32 s93, s93, 16
	s_or_b32 s85, s85, s93
	s_mov_b64 s[100:101], 0
	s_branch .LBB0_140

.LBB0_143:
	s_and_b32 s93, s32, 3
	s_add_i32 s32, s32, 1
	s_mov_b32 s97, 0
	s_cmp_lg_u32 s93, 0
	s_cbranch_scc1 .Leng_not0
	s_mov_b64 s[100:101], 0
	s_bitcmp1_b32 s85, 31
	s_cbranch_scc1 .Leng_grpB
	s_lshr_b32 s93, s85, 16
	s_cmp_ge_u32 s93, 0x100
	s_cbranch_scc0 .Leng_Aok
	s_or_b32 s85, s80, 0x80000000
	s_branch .Leng_grpB
.Leng_Aok:
	s_cmp_lt_u32 s93, 0x80
	s_cbranch_scc0 .Leng_gate
	v_readlane_b32 s98, v245, 2
	v_readlane_b32 s99, v245, 3
	s_movk_i32 s100, 0x80
	s_branch .Leng_mat
.Leng_gate:
	v_readlane_b32 s98, v245, 0
	v_readlane_b32 s99, v245, 1
	s_sub_i32 s93, s93, 0x80
	s_mov_b32 s100, 0

; __device__ __forceinline__ unsigned cvt_pk_bf16(float lo, float hi) { const cvt_f2 v = {lo, hi}; return __builtin_bit_cast(unsigned, __builtin_convertvector(v, cvt_b2)); }
; #define GAS __attribute__((address_space(1)))
; #define LAS __attribute__((address_space(3)))
; #define LDS_WAIT() asm volatile("s_waitcnt lgkmcnt(0)" ::: "memory")
; __device__ __forceinline__ void conv_load(const ConvItem& it, int lane, f32x4 (&v)[4]) {
;     const int lk = lane >> 3, ln = (lane & 7) * 4;
; #pragma unroll
;     for (int i = 0; i < 4; ++i) v[i] = __builtin_nontemporal_load((const GAS f32x4*)(it.W + (size_t)(it.k0 + 8 * i + lk) * it.N + it.n0 + ln));
; }
; __device__ __forceinline__ void conv_store(const ConvItem& it, int lane, const f32x4 (&v)[4], LAS bf16* scr) {
;     const int lk = lane >> 3, ln = (lane & 7) * 4;
; #pragma unroll
;     for (int i = 0; i < 4; ++i) { const float gk = it.kgain ? it.kgain[it.k0 + 8 * i + lk] : 1.0f; LAS unsigned* p = (LAS unsigned*)(scr + (8 * i + lk) * 34 + ln); p[0] = pg8::cvt_pk_bf16(v[i][0] * gk, v[i][1] * gk); p[1] = pg8::cvt_pk_bf16(v[i][2] * gk, v[i][3] * gk); }
;     LDS_WAIT(); asm volatile("" ::: "memory");
.Leng_grpB:
	s_and_b32 s93, s85, 0x7fffffff
	s_cmp_ge_u32 s93, 0x8000
	s_cbranch_scc1 .Leng_done
	s_lshr_b32 s97, s93, 13
	s_cmp_eq_u32 s97, 0
	s_cbranch_scc0 .Leng_B1
	v_readlane_b32 s98, v245, 6
	v_readlane_b32 s99, v245, 7
	v_readlane_b32 s100, v244, 2
	v_readlane_b32 s101, v244, 3
	s_mov_b32 s97, 0
	s_branch .Leng_Bm
.Leng_B1:
	s_cmp_eq_u32 s97, 1
	s_cbranch_scc0 .Leng_B2
	v_readlane_b32 s98, v245, 8
	v_readlane_b32 s99, v245, 9
	v_readlane_b32 s100, v244, 2
	v_readlane_b32 s101, v244, 3
	s_sub_i32 s93, s93, 0x2000
	s_movk_i32 s97, 0x1000
	s_branch .Leng_Bm
.Leng_B2:
	v_readlane_b32 s98, v245, 10
	v_readlane_b32 s99, v245, 11
	v_readlane_b32 s100, v244, 4
	v_readlane_b32 s101, v244, 5
	s_sub_i32 s93, s93, 0x4000
	s_mov_b32 s97, 0
.Leng_Bm:
	v_lshrrev_b32_e32 v254, 3, v1
	v_lshlrev_b32_e32 v254, 14, v254
	v_and_b32_e32 v255, 7, v1
	v_lshl_add_u32 v254, v255, 4, v254
	s_add_u32 s100, s100, s97
	s_addc_u32 s101, s101, 0
	s_lshr_b32 s97, s93, 7
	s_and_b32 s93, s93, 0x7f
	s_lshl_b32 s97, s97, 6
	s_add_u32 s100, s100, s97
	s_addc_u32 s101, s101, 0
	s_lshl_b32 s97, s97, 13
	s_add_u32 s98, s98, s97
	s_addc_u32 s99, s99, 0
	s_lshl_b32 s97, s93, 7
	s_add_u32 s98, s98, s97
	s_addc_u32 s99, s99, 0
	s_lshl_b32 s97, s93, 18
	s_add_u32 s100, s100, s97
	s_addc_u32 s101, s101, 0
	s_or_b32 s100, s100, 1
	global_load_dwordx4 v[232:235], v254, s[98:99] nt
	s_add_u32 s98, s98, 0x20000
	s_addc_u32 s99, s99, 0
	global_load_dwordx4 v[236:239], v254, s[98:99] nt
	s_add_u32 s98, s98, 0x20000
	s_addc_u32 s99, s99, 0
	global_load_dwordx4 v[240:243], v254, s[98:99] nt
	s_add_u32 s98, s98, 0x20000
	s_addc_u32 s99, s99, 0
	global_load_dwordx4 v[246:249], v254, s[98:99] nt
	s_mov_b32 s97, 4
	s_branch .Leng_done
.Leng_not0:
	s_cmp_eq_u64 s[100:101], 0
	s_cbranch_scc1 .Leng_adv
	s_cmp_lg_u32 s93, 1
	s_cbranch_scc1 .Leng_not1
	v_readlane_b32 s93, v244, 10
	v_lshrrev_b32_e32 v254, 3, v1
	v_mul_u32_u24_e32 v254, 0x44, v254
	v_and_b32_e32 v255, 7, v1
	v_lshl_add_u32 v254, v255, 3, v254
	s_mulk_i32 s93, 0x900
	s_add_i32 s93, s93, 0x22400
	v_add_u32_e32 v254, s93, v254
	v_add_u32_e32 v255, 0x440, v254
	s_bitcmp1_b32 s100, 0
	s_cbranch_scc1 .Leng_nogain
	v_mul_f32_e32 v232, v250, v232
	v_mul_f32_e32 v233, v250, v233
	v_mul_f32_e32 v234, v250, v234
	v_mul_f32_e32 v235, v250, v235
	v_cvt_pk_bf16_f32 v232, v232, v233
	v_cvt_pk_bf16_f32 v233, v234, v235
	ds_write2_b32 v254, v232, v233 offset1:1
	v_mul_f32_e32 v236, v251, v236
	v_mul_f32_e32 v237, v251, v237
	v_mul_f32_e32 v238, v251, v238
	v_mul_f32_e32 v239, v251, v239
	v_cvt_pk_bf16_f32 v236, v236, v237
	v_cvt_pk_bf16_f32 v237, v238, v239
	ds_write2_b32 v254, v236, v237 offset0:136 offset1:137
	v_mul_f32_e32 v240, v252, v240
	v_mul_f32_e32 v241, v252, v241
	v_mul_f32_e32 v242, v252, v242
	v_mul_f32_e32 v243, v252, v243
	v_cvt_pk_bf16_f32 v240, v240, v241
	v_cvt_pk_bf16_f32 v241, v242, v243
	ds_write2_b32 v255, v240, v241 offset1:1
	v_mul_f32_e32 v246, v253, v246
	v_mul_f32_e32 v247, v253, v247
	v_mul_f32_e32 v248, v253, v248
	v_mul_f32_e32 v249, v253, v249
	v_cvt_pk_bf16_f32 v246, v246, v247
	v_cvt_pk_bf16_f32 v247, v248, v249
	ds_write2_b32 v255, v246, v247 offset0:136 offset1:137
	s_branch .Leng_done
.Leng_nogain:
	v_cvt_pk_bf16_f32 v232, v232, v233
	v_cvt_pk_bf16_f32 v233, v234, v235
	ds_write2_b32 v254, v232, v233 offset1:1
	v_cvt_pk_bf16_f32 v236, v236, v237
	v_cvt_pk_bf16_f32 v237, v238, v239
	ds_write2_b32 v254, v236, v237 offset0:136 offset1:137
	v_cvt_pk_bf16_f32 v240, v240, v241
	v_cvt_pk_bf16_f32 v241, v242, v243
	ds_write2_b32 v255, v240, v241 offset1:1
	v_cvt_pk_bf16_f32 v246, v246, v247
	v_cvt_pk_bf16_f32 v247, v248, v249
	ds_write2_b32 v255, v246, v247 offset0:136 offset1:137
	s_branch .Leng_done

; #define PG8_STAGE(bufoff, gbase, voff) do { _Pragma("unroll") for (int _i = 0; _i < 2; ++_i) \
;         __builtin_amdgcn_global_load_lds((const unsigned*)((const char*)(gbase) + (voff)[_i]), (PG8_LAS unsigned*)(lds + (bufoff) + ldsw + _i * 8192), 16, 0, 0); } while (0)
; #define PG8_LDA(dst, b, h) do { _Pragma("unroll") for (int m = 0; m < 4; ++m) _Pragma("unroll") for (int k = 0; k < 2; ++k) dst[m][k] = *(const PG8_LAS bf16x8*)(lds + PG8_SA(b, h) + aoff + m * 2048 + k * 1024); } while (0)
; #define PG8_LDB(dst, b, h) do { _Pragma("unroll") for (int n = 0; n < 2; ++n) _Pragma("unroll") for (int k = 0; k < 2; ++k) dst[n][k] = *(const PG8_LAS bf16x8*)(lds + PG8_SB(b, h) + boff + n * 2048 + k * 1024); } while (0)
; #define PG8_MMA(ai, bj, At, Bt) do { __builtin_amdgcn_s_setprio(3); _Pragma("unroll") for (int m = 0; m < 4; ++m) _Pragma("unroll") for (int n = 0; n < 2; ++n) _Pragma("unroll") for (int k = 0; k < 2; ++k) \
;         acc[ai][bj][m][n] = __builtin_amdgcn_mfma_f32_16x16x32_bf16(Bt[n][k], At[m][k], acc[ai][bj][m][n], 0, 0, 0); __builtin_amdgcn_s_setprio(0); } while (0)
; #define PG8_BAR __builtin_amdgcn_s_barrier()
; template <class Epi, class Sched, bool ALIGN_EPI = false, bool SP2 = false>
; __device__ __forceinline__ void gemm_phase(PG8_LAS unsigned char* lds, const Gemm g, const Sched& S, const Epi& E) {
;     ...
;             PG8_LDB(B0, 0, 0); PG8_LDB(B1, 0, 1); PG8_SCHED; PG8_LDA(At, 0, 0); PG8_STAGE(PG8_SA(1, 1), a1 + hstepA, voffA);
;             PG8_WAIT_V(8); PG8_WAIT_L(0); PG8_BAR; PG8_MMA(0, 0, At, B0); PG8_MMA(0, 1, At, B1); PG8_BAR; PG8_SCHED;
; __device__ __forceinline__ void conv_store(const ConvItem& it, int lane, const f32x4 (&v)[4], LAS bf16* scr) {
;     ...
;     const int c = lane & 3;
; #pragma unroll
;     for (int j = 0; j < 2; ++j) { const int n = (lane >> 2) + 16 * j; const LAS bf16* sp = scr + (8 * c) * 34 + n;
;         v4u o; o.x = (unsigned)sp[0] | ((unsigned)sp[34] << 16); o.y = (unsigned)sp[68] | ((unsigned)sp[102] << 16); o.z = (unsigned)sp[136] | ((unsigned)sp[170] << 16); o.w = (unsigned)sp[204] | ((unsigned)sp[238] << 16);
;         const int ng = it.n0 + n; const int row = it.rowmode == 0 ? ng : ((ng >> 7) * 256 + (it.rowmode == 2 ? 128 : 0) + (ng & 127));
;         __builtin_nontemporal_store(o, (GAS v4u*)(it.WT + (size_t)row * it.ldt + it.k0 + 8 * c)); }
;     LDS_WAIT(); asm volatile("" ::: "memory");
.Leng_st3:
	v_and_b32_e32 v254, 3, v1
	v_lshlrev_b32_e32 v254, 4, v254
	v_lshrrev_b32_e32 v255, 2, v1
	v_lshl_add_u32 v254, v255, 13, v254
	v_add_u32_e32 v255, 0x20000, v254
	v_lshl_or_b32 v232, v233, 16, v232
	v_lshl_or_b32 v233, v235, 16, v234
	v_lshl_or_b32 v234, v237, 16, v236
	v_lshl_or_b32 v235, v239, 16, v238
	v_lshl_or_b32 v236, v241, 16, v240
	v_lshl_or_b32 v237, v243, 16, v242
	v_lshl_or_b32 v238, v247, 16, v246
	v_lshl_or_b32 v239, v249, 16, v248
	s_and_b32 s98, s100, -2
	s_mov_b32 s99, s101
	global_store_dwordx4 v254, v[232:235], s[98:99] nt
	global_store_dwordx4 v255, v[236:239], s[98:99] nt
	s_mov_b32 s97, 2
.Leng_adv:
	s_cmp_lg_u32 s93, 3
	s_cbranch_scc1 .Leng_done
	s_bitcmp1_b32 s85, 31
	s_cbranch_scc0 .Leng_advA
	s_add_i32 s85, s85, 0x800
	s_branch .Leng_done
.Leng_advA:
	s_add_i32 s85, s85, 0x50148
	s_and_b32 s93, s85, 0xffff
	s_cmp_ge_u32 s93, 0x158
	s_cbranch_scc0 .Leng_done
	s_add_i32 s85, s85, 0xfea8
.Leng_done:
	ds_read_b128 v[130:133], v167
	ds_read_b128 v[134:137], v167 offset:1024
	ds_read_b128 v[156:159], v167 offset:2048
	ds_read_b128 v[172:175], v167 offset:3072
	ds_read_b128 v[176:179], v168
	ds_read_b128 v[180:183], v168 offset:1024
	ds_read_b128 v[184:187], v168 offset:2048
	ds_read_b128 v[188:191], v168 offset:3072
	s_add_u32 s8, s6, 0xfff00080
	s_addc_u32 s9, s7, -1
	s_cmp_eq_u32 s45, 60
	s_cselect_b32 s37, s1, s9
	s_cselect_b32 s36, s14, s8
	s_cselect_b32 s9, s25, s44
	s_cselect_b32 s8, s27, s33
	v_lshl_add_u64 v[160:161], s[6:7], 0, v[148:149]
	s_add_i32 m0, s55, 0xc000
	ds_read_b128 v[192:195], v169
	ds_read_b128 v[196:199], v169 offset:1024
	ds_read_b128 v[200:203], v169 offset:2048
	ds_read_b128 v[204:207], v169 offset:3072
	ds_read_b128 v[208:211], v169 offset:4096
	ds_read_b128 v[212:215], v169 offset:5120
	ds_read_b128 v[216:219], v169 offset:6144
	ds_read_b128 v[220:223], v169 offset:7168
	global_load_lds_dwordx4 v[160:161], off
	v_lshl_add_u64 v[160:161], s[6:7], 0, v[150:151]
	s_add_i32 m0, s55, 0xe000
	s_nop 0
	global_load_lds_dwordx4 v[160:161], off
	s_cmp_eq_u32 s97, 0
	s_cbranch_scc1 .Lengw1_a
	s_cmp_eq_u32 s97, 2
	s_cbranch_scc1 .Lengw1_b
	s_cmp_eq_u32 s97, 4
	s_cbranch_scc1 .Lengw1_c
	s_waitcnt vmcnt(16)
	s_branch .Lengw1_e
.Lengw1_c:
	s_waitcnt vmcnt(12)
	s_branch .Lengw1_e

; #define PG8_STAGE(bufoff, gbase, voff) do { _Pragma("unroll") for (int _i = 0; _i < 2; ++_i) \
;         __builtin_amdgcn_global_load_lds((const unsigned*)((const char*)(gbase) + (voff)[_i]), (PG8_LAS unsigned*)(lds + (bufoff) + ldsw + _i * 8192), 16, 0, 0); } while (0)
; #define PG8_LDA(dst, b, h) do { _Pragma("unroll") for (int m = 0; m < 4; ++m) _Pragma("unroll") for (int k = 0; k < 2; ++k) dst[m][k] = *(const PG8_LAS bf16x8*)(lds + PG8_SA(b, h) + aoff + m * 2048 + k * 1024); } while (0)
; #define PG8_MMA(ai, bj, At, Bt) do { __builtin_amdgcn_s_setprio(3); _Pragma("unroll") for (int m = 0; m < 4; ++m) _Pragma("unroll") for (int n = 0; n < 2; ++n) _Pragma("unroll") for (int k = 0; k < 2; ++k) \
;         acc[ai][bj][m][n] = __builtin_amdgcn_mfma_f32_16x16x32_bf16(Bt[n][k], At[m][k], acc[ai][bj][m][n], 0, 0, 0); __builtin_amdgcn_s_setprio(0); } while (0)
; #define PG8_WAIT_V(n) asm volatile("s_waitcnt vmcnt(" #n ")" ::: "memory")
; #define PG8_WAIT_L(n) asm volatile("s_waitcnt lgkmcnt(" #n ")" ::: "memory")
; #define PG8_BAR __builtin_amdgcn_s_barrier()
; #define PG8_SCHED __builtin_amdgcn_sched_barrier(0)
; template <class Epi, class Sched, bool ALIGN_EPI = false, bool SP2 = false>
; __device__ __forceinline__ void gemm_phase(PG8_LAS unsigned char* lds, const Gemm g, const Sched& S, const Epi& E) {
;     ...
;             PG8_WAIT_V(8); PG8_WAIT_L(0); PG8_BAR; PG8_MMA(0, 0, At, B0); PG8_MMA(0, 1, At, B1); PG8_BAR; PG8_SCHED;
;             PG8_LDA(At, 0, 1); PG8_STAGE(PG8_SB(0, 0), b2, voffB); PG8_STAGE(PG8_SB(0, 1), b2 + hstepB, voffB); PG8_STAGE(PG8_SA(0, 0), a2, voffA);
;             PG8_WAIT_V(8); PG8_WAIT_L(0); PG8_BAR; PG8_MMA(1, 0, At, B0); PG8_MMA(1, 1, At, B1); PG8_BAR; PG8_SCHED;
.Lengw1_e:
	s_waitcnt lgkmcnt(0)
	s_barrier
	s_setprio 3
	s_waitcnt lgkmcnt(0)
	v_mfma_f32_16x16x32_bf16 v[126:129], v[130:133], v[192:195], v[126:129]
	v_mfma_f32_16x16x32_bf16 v[118:121], v[156:159], v[192:195], v[118:121]
	v_mfma_f32_16x16x32_bf16 v[110:113], v[130:133], v[200:203], v[110:113]
	v_mfma_f32_16x16x32_bf16 v[102:105], v[156:159], v[200:203], v[102:105]
	v_mfma_f32_16x16x32_bf16 v[94:97], v[130:133], v[208:211], v[94:97]
	v_mfma_f32_16x16x32_bf16 v[86:89], v[156:159], v[208:211], v[86:89]
	v_mfma_f32_16x16x32_bf16 v[78:81], v[130:133], v[216:219], v[78:81]
	v_mfma_f32_16x16x32_bf16 v[70:73], v[156:159], v[216:219], v[70:73]
	v_mfma_f32_16x16x32_bf16 v[126:129], v[134:137], v[196:199], v[126:129]
	v_mfma_f32_16x16x32_bf16 v[118:121], v[172:175], v[196:199], v[118:121]
	v_mfma_f32_16x16x32_bf16 v[110:113], v[134:137], v[204:207], v[110:113]
	v_mfma_f32_16x16x32_bf16 v[102:105], v[172:175], v[204:207], v[102:105]
	v_mfma_f32_16x16x32_bf16 v[94:97], v[134:137], v[212:215], v[94:97]
	v_mfma_f32_16x16x32_bf16 v[86:89], v[172:175], v[212:215], v[86:89]
	v_mfma_f32_16x16x32_bf16 v[78:81], v[134:137], v[220:223], v[78:81]
	v_mfma_f32_16x16x32_bf16 v[70:73], v[172:175], v[220:223], v[70:73]
	s_setprio 0
	s_setprio 3
	v_mfma_f32_16x16x32_bf16 v[122:125], v[176:179], v[192:195], v[122:125]
	v_mfma_f32_16x16x32_bf16 v[114:117], v[184:187], v[192:195], v[114:117]
	v_mfma_f32_16x16x32_bf16 v[106:109], v[176:179], v[200:203], v[106:109]
	v_mfma_f32_16x16x32_bf16 v[98:101], v[184:187], v[200:203], v[98:101]
	v_mfma_f32_16x16x32_bf16 v[90:93], v[176:179], v[208:211], v[90:93]
	v_mfma_f32_16x16x32_bf16 v[82:85], v[184:187], v[208:211], v[82:85]
	v_mfma_f32_16x16x32_bf16 v[74:77], v[176:179], v[216:219], v[74:77]
	v_mfma_f32_16x16x32_bf16 v[66:69], v[184:187], v[216:219], v[66:69]
	v_mfma_f32_16x16x32_bf16 v[122:125], v[180:183], v[196:199], v[122:125]
	v_mfma_f32_16x16x32_bf16 v[114:117], v[188:191], v[196:199], v[114:117]
	v_mfma_f32_16x16x32_bf16 v[106:109], v[180:183], v[204:207], v[106:109]
	v_mfma_f32_16x16x32_bf16 v[98:101], v[188:191], v[204:207], v[98:101]
	v_mfma_f32_16x16x32_bf16 v[90:93], v[180:183], v[212:215], v[90:93]
	v_mfma_f32_16x16x32_bf16 v[82:85], v[188:191], v[212:215], v[82:85]
	v_mfma_f32_16x16x32_bf16 v[74:77], v[180:183], v[220:223], v[74:77]
	v_mfma_f32_16x16x32_bf16 v[66:69], v[188:191], v[220:223], v[66:69]
	s_setprio 0
	s_barrier
	s_add_i32 s56, s83, s66
	v_lshl_add_u64 v[160:161], s[8:9], 0, v[140:141]
	s_mov_b32 m0, s56
	ds_read_b128 v[192:195], v169 offset:16384
	ds_read_b128 v[196:199], v169 offset:17408
	ds_read_b128 v[200:203], v169 offset:18432
	ds_read_b128 v[204:207], v169 offset:19456
	ds_read_b128 v[208:211], v169 offset:20480
	ds_read_b128 v[212:215], v169 offset:21504
	ds_read_b128 v[216:219], v169 offset:22528
	ds_read_b128 v[220:223], v169 offset:23552
	global_load_lds_dwordx4 v[160:161], off
	s_add_i32 m0, s56, 0x2000
	s_add_u32 s56, s8, 0x100000
	v_lshl_add_u64 v[224:225], s[8:9], 0, v[144:145]
	s_addc_u32 s57, s9, 0
	s_add_i32 s58, s89, s66
	global_load_lds_dwordx4 v[224:225], off
	v_lshl_add_u64 v[226:227], s[56:57], 0, v[140:141]
	s_mov_b32 m0, s58
	v_lshl_add_u64 v[228:229], s[36:37], 0, v[142:143]
	global_load_lds_dwordx4 v[226:227], off
	v_lshl_add_u64 v[226:227], s[56:57], 0, v[144:145]
	s_add_i32 m0, s58, 0x2000
	s_nop 0
	global_load_lds_dwordx4 v[226:227], off
	v_lshl_add_u64 v[226:227], s[36:37], 0, v[138:139]
	s_mov_b32 m0, s55
	s_nop 0
	global_load_lds_dwordx4 v[226:227], off
	s_mov_b32 m0, s67
	s_nop 0
	global_load_lds_dwordx4 v[228:229], off
	s_cmp_eq_u32 s97, 0
	s_cbranch_scc1 .Lengw2_a
	s_cmp_eq_u32 s97, 2
	s_cbranch_scc1 .Lengw2_b
	s_cmp_eq_u32 s97, 4
	s_cbranch_scc1 .Lengw2_c
	s_waitcnt vmcnt(16)
	s_branch .Lengw2_e
